# 6 seams XCD-local or flush-free (P3-P4 global execution barrier without L2 writeback), P5 conv and scan mapped to the XCD owning the batch, split-phase counter orders P5 reads before P8 ACT writes
# speedup vs baseline: 1.0119x; 1.0119x over previous
.LBB0_298:
	s_cmp_gt_i32 s31, 4
	s_cselect_b64 s[0:1], -1, 0
	s_and_b64 s[2:3], s[4:5], s[0:1]
	s_andn2_b64 vcc, exec, s[2:3]
	s_cbranch_vccnz .LBB0_332
	s_waitcnt vmcnt(0)
	v_cmp_eq_u32_e32 vcc, 0, v0
	s_waitcnt lgkmcnt(0)
	s_barrier
	v_mov_b32_e32 v1, s88
	ds_read_b32 v2, v1 offset:8
	s_waitcnt lgkmcnt(0)
	v_readfirstlane_b32 s98, v2
	s_cmp_eq_u32 s98, 1
	s_cbranch_scc1 .Llb_loc_s3
	s_and_saveexec_b64 s[2:3], vcc
	s_cbranch_execz .LBB0_331
	v_mov_b32_e32 v1, s88
	s_waitcnt vmcnt(0) expcnt(0) lgkmcnt(0)
	ds_read_b32 v2, v1
	ds_read_b32 v1, v1 offset:4
	s_waitcnt lgkmcnt(1)
	v_cmp_ne_u32_e32 vcc, 0, v2
	s_cbranch_vccnz .LBB0_315
	v_readlane_b32 s4, v254, 8
	v_readlane_b32 s5, v254, 9
	s_load_dwordx2 s[10:11], s[4:5], 0x4
	s_add_u32 s4, s28, 0x4200
	s_addc_u32 s5, s29, 0
	s_add_u32 s6, s28, 0x4400
	s_addc_u32 s7, s29, 0
	s_waitcnt lgkmcnt(0)
	s_mul_i32 s16, s10, s25
	s_add_u32 s10, s28, 0x4500
	s_mul_i32 s16, s16, s11
	s_addc_u32 s11, s29, 0
	s_add_u32 s12, s28, 0x4600
	s_addc_u32 s13, s29, 0
	s_add_u32 s14, s28, 0x4700
	s_addc_u32 s15, s29, 0
	s_add_u32 s44, s28, 0x4800
	s_addc_u32 s45, s29, 0
	s_add_u32 s48, s28, 0x4900
	s_addc_u32 s49, s29, 0
	s_add_u32 s50, s28, 0x4a00
	s_addc_u32 s51, s29, 0
	s_add_u32 s52, s28, 0x4b00
	s_addc_u32 s53, s29, 0
	s_add_u32 s66, s28, 0x4c00
	s_addc_u32 s67, s29, 0
	s_add_u32 s68, s28, 0x4d00
	s_addc_u32 s69, s29, 0
	s_add_u32 s70, s28, 0x4e00
	s_addc_u32 s71, s29, 0
	s_add_u32 s72, s28, 0x4f00
	s_addc_u32 s73, s29, 0
	s_add_u32 s74, s28, 0x5000
	s_addc_u32 s75, s29, 0
	s_add_u32 s76, s28, 0x5100
	s_addc_u32 s77, s29, 0
	s_add_u32 s78, s28, 0x5200
	s_addc_u32 s79, s29, 0
	s_add_u32 s80, s28, 0x5300
	s_addc_u32 s81, s29, 0
	s_mov_b32 s17, 1
	v_mov_b32_e32 v17, 0
	s_branch .LBB0_303

.Llb_loc_s3:
	s_and_saveexec_b64 s[2:3], vcc
	s_cbranch_execz .Llb_done_s3
	v_mov_b32_e32 v1, s88
	ds_read_b32 v2, v1
	v_readlane_b32 s4, v254, 14
	v_readlane_b32 s10, v254, 12
	v_readlane_b32 s11, v254, 13
	s_lshl_b32 s4, s4, 8
	s_add_u32 s4, s10, s4
	s_addc_u32 s5, s11, 0
	v_mov_b32_e32 v3, 0x2400
	v_mov_b32_e32 v4, 1
	global_atomic_add v3, v4, s[4:5]
	v_mov_b32_e32 v5, 0x240c
	global_atomic_add v5, v4, s[10:11]
	s_waitcnt lgkmcnt(0)
	v_mul_lo_u32 v2, v2, 2
	s_mov_b32 s99, 0

.Llb_acq_s3:
	v_mov_b32_e32 v5, 0x240c
	s_mov_b32 s99, 0
.Llb_g3_s3:
	global_load_dword v4, v5, s[10:11] sc1
	s_waitcnt vmcnt(0)
	v_cmp_le_u32_e32 vcc, s25, v4
	s_cbranch_vccnz .Llb_g3d_s3
	s_sleep 1
	s_add_i32 s99, s99, 1
	s_cmp_lt_u32 s99, 0x40000
	s_cbranch_scc1 .Llb_g3_s3

.LBB0_387:
	s_add_u32 s98, s28, 0xf000000
	s_addc_u32 s99, s29, 0
	s_waitcnt vmcnt(0)
	v_pk_fma_f32 v[120:121], v[120:121], v[186:187], v[140:141] op_sel_hi:[1,0,1]
	v_pk_fma_f32 v[118:119], v[118:119], v[186:187], v[138:139] op_sel_hi:[1,0,1]
	v_pk_fma_f32 v[114:115], v[114:115], v[186:187], v[130:131] op_sel_hi:[1,0,1]
	v_pk_mul_f32 v[120:121], v[120:121], s[78:79] op_sel_hi:[1,0]
	v_pk_mul_f32 v[118:119], v[118:119], s[78:79] op_sel_hi:[1,0]
	v_pk_fma_f32 v[116:117], v[116:117], v[186:187], v[132:133] op_sel_hi:[1,0,1]
	v_pk_mul_f32 v[114:115], v[114:115], s[78:79] op_sel_hi:[1,0]
	v_exp_f32_e32 v118, v118
	v_exp_f32_e32 v120, v120
	v_exp_f32_e32 v121, v121
	v_exp_f32_e32 v119, v119
	v_pk_mul_f32 v[116:117], v[116:117], s[78:79] op_sel_hi:[1,0]
	v_exp_f32_e32 v114, v114
	v_exp_f32_e32 v115, v115
	v_pk_fma_f32 v[102:103], v[102:103], v[184:185], v[138:139] op_sel_hi:[1,0,1]
	v_exp_f32_e32 v116, v116
	v_exp_f32_e32 v117, v117
	v_pk_mul_f32 v[102:103], v[102:103], s[78:79] op_sel_hi:[1,0]
	v_pk_fma_f32 v[100:101], v[100:101], v[184:185], v[132:133] op_sel_hi:[1,0,1]
	v_pk_fma_f32 v[98:99], v[98:99], v[184:185], v[130:131] op_sel_hi:[1,0,1]
	v_exp_f32_e32 v102, v102
	v_exp_f32_e32 v103, v103
	v_pk_mul_f32 v[100:101], v[100:101], s[78:79] op_sel_hi:[1,0]
	v_pk_mul_f32 v[98:99], v[98:99], s[78:79] op_sel_hi:[1,0]
	v_pk_fma_f32 v[86:87], v[86:87], v[182:183], v[138:139] op_sel_hi:[1,0,1]
	v_pk_fma_f32 v[104:105], v[104:105], v[184:185], v[140:141] op_sel_hi:[1,0,1]
	v_exp_f32_e32 v98, v98
	v_exp_f32_e32 v100, v100
	v_exp_f32_e32 v101, v101
	v_exp_f32_e32 v99, v99
	v_pk_mul_f32 v[86:87], v[86:87], s[78:79] op_sel_hi:[1,0]
	v_pk_fma_f32 v[84:85], v[84:85], v[182:183], v[132:133] op_sel_hi:[1,0,1]
	v_pk_fma_f32 v[82:83], v[82:83], v[182:183], v[130:131] op_sel_hi:[1,0,1]
	v_pk_add_f32 v[120:121], v[120:121], 1.0 op_sel_hi:[1,0]
	v_pk_add_f32 v[118:119], v[118:119], 1.0 op_sel_hi:[1,0]
	v_pk_add_f32 v[114:115], v[114:115], 1.0 op_sel_hi:[1,0]
	v_pk_mul_f32 v[104:105], v[104:105], s[78:79] op_sel_hi:[1,0]
	v_exp_f32_e32 v86, v86
	v_exp_f32_e32 v87, v87
	v_pk_mul_f32 v[84:85], v[84:85], s[78:79] op_sel_hi:[1,0]
	v_pk_mul_f32 v[82:83], v[82:83], s[78:79] op_sel_hi:[1,0]
	v_pk_fma_f32 v[70:71], v[70:71], v[180:181], v[138:139] op_sel_hi:[1,0,1]
	v_rcp_f32_e32 v118, v118
	v_rcp_f32_e32 v119, v119
	v_rcp_f32_e32 v120, v120
	v_rcp_f32_e32 v121, v121
	v_pk_add_f32 v[116:117], v[116:117], 1.0 op_sel_hi:[1,0]
	v_rcp_f32_e32 v114, v114
	v_rcp_f32_e32 v115, v115
	v_exp_f32_e32 v104, v104
	v_exp_f32_e32 v105, v105
	v_pk_fma_f32 v[88:89], v[88:89], v[182:183], v[140:141] op_sel_hi:[1,0,1]
	v_exp_f32_e32 v82, v82
	v_exp_f32_e32 v84, v84
	v_exp_f32_e32 v85, v85
	v_exp_f32_e32 v83, v83
	v_pk_mul_f32 v[70:71], v[70:71], s[78:79] op_sel_hi:[1,0]
	v_pk_fma_f32 v[68:69], v[68:69], v[180:181], v[132:133] op_sel_hi:[1,0,1]
	v_pk_fma_f32 v[66:67], v[66:67], v[180:181], v[130:131] op_sel_hi:[1,0,1]
	s_lshl_b32 s0, s80, 7
	v_rcp_f32_e32 v116, v116
	v_rcp_f32_e32 v117, v117
	v_pk_add_f32 v[102:103], v[102:103], 1.0 op_sel_hi:[1,0]
	v_pk_mul_f32 v[88:89], v[88:89], s[78:79] op_sel_hi:[1,0]
	v_exp_f32_e32 v70, v70
	v_exp_f32_e32 v71, v71
	v_pk_mul_f32 v[68:69], v[68:69], s[78:79] op_sel_hi:[1,0]
	v_pk_mul_f32 v[66:67], v[66:67], s[78:79] op_sel_hi:[1,0]
	v_pk_fma_f32 v[54:55], v[54:55], v[152:153], v[138:139] op_sel_hi:[1,0,1]
	s_or_b32 s0, s0, s73
	v_rcp_f32_e32 v102, v102
	v_rcp_f32_e32 v103, v103
	v_pk_add_f32 v[100:101], v[100:101], 1.0 op_sel_hi:[1,0]
	v_pk_add_f32 v[98:99], v[98:99], 1.0 op_sel_hi:[1,0]
	v_exp_f32_e32 v88, v88
	v_exp_f32_e32 v89, v89
	v_pk_fma_f32 v[72:73], v[72:73], v[180:181], v[140:141] op_sel_hi:[1,0,1]
	v_exp_f32_e32 v66, v66
	v_exp_f32_e32 v68, v68
	v_exp_f32_e32 v69, v69
	v_exp_f32_e32 v67, v67
	v_pk_mul_f32 v[54:55], v[54:55], s[78:79] op_sel_hi:[1,0]
	v_pk_fma_f32 v[52:53], v[52:53], v[152:153], v[132:133] op_sel_hi:[1,0,1]
	v_pk_fma_f32 v[50:51], v[50:51], v[152:153], v[130:131] op_sel_hi:[1,0,1]
	v_add_u32_e32 v178, s0, v178
	v_pk_fma_f32 v[128:129], v[128:129], v[186:187], v[144:145] op_sel_hi:[1,0,1]
	v_pk_fma_f32 v[126:127], v[126:127], v[186:187], v[142:143] op_sel_hi:[1,0,1]
	v_pk_fma_f32 v[122:123], v[122:123], v[186:187], v[134:135] op_sel_hi:[1,0,1]
	v_rcp_f32_e32 v98, v98
	v_rcp_f32_e32 v100, v100
	v_rcp_f32_e32 v101, v101
	v_rcp_f32_e32 v99, v99
	v_pk_add_f32 v[86:87], v[86:87], 1.0 op_sel_hi:[1,0]
	v_pk_mul_f32 v[72:73], v[72:73], s[78:79] op_sel_hi:[1,0]
	v_exp_f32_e32 v54, v54
	v_exp_f32_e32 v55, v55
	v_pk_mul_f32 v[52:53], v[52:53], s[78:79] op_sel_hi:[1,0]
	v_pk_mul_f32 v[50:51], v[50:51], s[78:79] op_sel_hi:[1,0]
	v_pk_fma_f32 v[38:39], v[38:39], v[150:151], v[138:139] op_sel_hi:[1,0,1]
	v_ashrrev_i32_e32 v179, 31, v178
	v_pk_fma_f32 v[124:125], v[124:125], v[186:187], v[136:137] op_sel_hi:[1,0,1]
	v_pk_mul_f32 v[120:121], v[128:129], v[120:121]
	v_pk_mul_f32 v[118:119], v[126:127], v[118:119]
	v_pk_mul_f32 v[114:115], v[122:123], v[114:115]
	v_pk_add_f32 v[104:105], v[104:105], 1.0 op_sel_hi:[1,0]
	v_rcp_f32_e32 v86, v86
	v_rcp_f32_e32 v87, v87
	v_pk_add_f32 v[84:85], v[84:85], 1.0 op_sel_hi:[1,0]
	v_pk_add_f32 v[82:83], v[82:83], 1.0 op_sel_hi:[1,0]
	v_exp_f32_e32 v72, v72
	v_exp_f32_e32 v73, v73
	v_pk_fma_f32 v[56:57], v[56:57], v[152:153], v[140:141] op_sel_hi:[1,0,1]
	v_exp_f32_e32 v50, v50
	v_exp_f32_e32 v52, v52
	v_exp_f32_e32 v53, v53
	v_exp_f32_e32 v51, v51
	v_pk_mul_f32 v[38:39], v[38:39], s[78:79] op_sel_hi:[1,0]
	v_pk_fma_f32 v[36:37], v[36:37], v[150:151], v[132:133] op_sel_hi:[1,0,1]
	v_pk_fma_f32 v[34:35], v[34:35], v[150:151], v[130:131] op_sel_hi:[1,0,1]
	v_pk_mul_f32 v[124:125], v[124:125], v[116:117]
	v_cvt_pk_bf16_f32 v116, v118, v119
	v_cvt_pk_bf16_f32 v117, v120, v121
	v_cvt_pk_bf16_f32 v118, v114, v115
	v_lshl_add_u64 v[120:121], s[98:99], 0, v[188:189]
	v_lshlrev_b64 v[114:115], 1, v[178:179]
	v_pk_fma_f32 v[110:111], v[110:111], v[184:185], v[142:143] op_sel_hi:[1,0,1]
	v_rcp_f32_e32 v104, v104
	v_rcp_f32_e32 v105, v105
	v_rcp_f32_e32 v82, v82
	v_rcp_f32_e32 v84, v84
	v_rcp_f32_e32 v85, v85
	v_rcp_f32_e32 v83, v83
	v_pk_add_f32 v[70:71], v[70:71], 1.0 op_sel_hi:[1,0]
	v_pk_mul_f32 v[56:57], v[56:57], s[78:79] op_sel_hi:[1,0]
	v_exp_f32_e32 v38, v38
	v_exp_f32_e32 v39, v39
	v_pk_mul_f32 v[36:37], v[36:37], s[78:79] op_sel_hi:[1,0]
	v_pk_mul_f32 v[34:35], v[34:35], s[78:79] op_sel_hi:[1,0]
	v_pk_fma_f32 v[22:23], v[22:23], v[148:149], v[138:139] op_sel_hi:[1,0,1]
	v_lshl_add_u64 v[120:121], v[120:121], 0, v[114:115]
	v_pk_fma_f32 v[108:109], v[108:109], v[184:185], v[136:137] op_sel_hi:[1,0,1]
	v_pk_fma_f32 v[106:107], v[106:107], v[184:185], v[134:135] op_sel_hi:[1,0,1]
	v_pk_mul_f32 v[102:103], v[110:111], v[102:103]
	v_pk_add_f32 v[88:89], v[88:89], 1.0 op_sel_hi:[1,0]
	v_rcp_f32_e32 v70, v70
	v_rcp_f32_e32 v71, v71
	v_pk_add_f32 v[68:69], v[68:69], 1.0 op_sel_hi:[1,0]
	v_pk_add_f32 v[66:67], v[66:67], 1.0 op_sel_hi:[1,0]
	v_exp_f32_e32 v56, v56
	v_exp_f32_e32 v57, v57
	v_pk_fma_f32 v[40:41], v[40:41], v[150:151], v[140:141] op_sel_hi:[1,0,1]
	v_exp_f32_e32 v34, v34
	v_exp_f32_e32 v36, v36
	v_exp_f32_e32 v37, v37
	v_exp_f32_e32 v35, v35
	v_pk_mul_f32 v[22:23], v[22:23], s[78:79] op_sel_hi:[1,0]
	v_pk_fma_f32 v[20:21], v[20:21], v[148:149], v[132:133] op_sel_hi:[1,0,1]
	v_pk_fma_f32 v[18:19], v[18:19], v[148:149], v[130:131] op_sel_hi:[1,0,1]
	v_cvt_pk_bf16_f32 v119, v124, v125
	global_store_dwordx4 v[120:121], v[116:119], off
	v_pk_mul_f32 v[108:109], v[108:109], v[100:101]
	v_pk_mul_f32 v[100:101], v[106:107], v[98:99]
	v_cvt_pk_bf16_f32 v98, v102, v103
	v_lshl_add_u64 v[102:103], s[98:99], 0, v[176:177]
	v_pk_fma_f32 v[94:95], v[94:95], v[182:183], v[142:143] op_sel_hi:[1,0,1]
	v_rcp_f32_e32 v88, v88
	v_rcp_f32_e32 v89, v89
	v_rcp_f32_e32 v66, v66
	v_rcp_f32_e32 v68, v68
	v_rcp_f32_e32 v69, v69
	v_rcp_f32_e32 v67, v67
	v_pk_add_f32 v[54:55], v[54:55], 1.0 op_sel_hi:[1,0]
	v_pk_mul_f32 v[40:41], v[40:41], s[78:79] op_sel_hi:[1,0]
	v_exp_f32_e32 v22, v22
	v_exp_f32_e32 v23, v23
	v_pk_mul_f32 v[20:21], v[20:21], s[78:79] op_sel_hi:[1,0]
	v_pk_mul_f32 v[18:19], v[18:19], s[78:79] op_sel_hi:[1,0]
	v_pk_fma_f32 v[6:7], v[6:7], v[146:147], v[138:139] op_sel_hi:[1,0,1]
	v_pk_fma_f32 v[112:113], v[112:113], v[184:185], v[144:145] op_sel_hi:[1,0,1]
	v_lshl_add_u64 v[102:103], v[102:103], 0, v[114:115]
	v_pk_fma_f32 v[92:93], v[92:93], v[182:183], v[136:137] op_sel_hi:[1,0,1]
	v_pk_fma_f32 v[90:91], v[90:91], v[182:183], v[134:135] op_sel_hi:[1,0,1]
	v_pk_mul_f32 v[86:87], v[94:95], v[86:87]
	v_pk_add_f32 v[72:73], v[72:73], 1.0 op_sel_hi:[1,0]
	v_rcp_f32_e32 v54, v54
	v_rcp_f32_e32 v55, v55
	v_pk_add_f32 v[52:53], v[52:53], 1.0 op_sel_hi:[1,0]
	v_pk_add_f32 v[50:51], v[50:51], 1.0 op_sel_hi:[1,0]
	v_exp_f32_e32 v40, v40
	v_exp_f32_e32 v41, v41
	v_pk_fma_f32 v[24:25], v[24:25], v[148:149], v[140:141] op_sel_hi:[1,0,1]
	v_exp_f32_e32 v18, v18
	v_exp_f32_e32 v20, v20
	v_exp_f32_e32 v21, v21
	v_exp_f32_e32 v19, v19
	v_pk_mul_f32 v[6:7], v[6:7], s[78:79] op_sel_hi:[1,0]
	v_pk_fma_f32 v[4:5], v[4:5], v[146:147], v[132:133] op_sel_hi:[1,0,1]
	v_pk_fma_f32 v[2:3], v[2:3], v[146:147], v[130:131] op_sel_hi:[1,0,1]
	v_pk_mul_f32 v[104:105], v[112:113], v[104:105]
	v_pk_mul_f32 v[92:93], v[92:93], v[84:85]
	v_cvt_pk_bf16_f32 v99, v104, v105
	v_cvt_pk_bf16_f32 v100, v100, v101
	v_cvt_pk_bf16_f32 v101, v108, v109
	global_store_dwordx4 v[102:103], v[98:101], off
	v_pk_mul_f32 v[84:85], v[90:91], v[82:83]
	v_cvt_pk_bf16_f32 v82, v86, v87
	v_lshl_add_u64 v[86:87], s[98:99], 0, v[174:175]
	v_pk_fma_f32 v[78:79], v[78:79], v[180:181], v[142:143] op_sel_hi:[1,0,1]
	v_rcp_f32_e32 v72, v72
	v_rcp_f32_e32 v73, v73
	v_rcp_f32_e32 v50, v50
	v_rcp_f32_e32 v52, v52
	v_rcp_f32_e32 v53, v53
	v_rcp_f32_e32 v51, v51
	v_pk_add_f32 v[38:39], v[38:39], 1.0 op_sel_hi:[1,0]
	v_pk_mul_f32 v[24:25], v[24:25], s[78:79] op_sel_hi:[1,0]
	v_exp_f32_e32 v6, v6
	v_exp_f32_e32 v7, v7
	v_pk_mul_f32 v[4:5], v[4:5], s[78:79] op_sel_hi:[1,0]
	v_pk_mul_f32 v[2:3], v[2:3], s[78:79] op_sel_hi:[1,0]
	v_pk_fma_f32 v[96:97], v[96:97], v[182:183], v[144:145] op_sel_hi:[1,0,1]
	v_lshl_add_u64 v[86:87], v[86:87], 0, v[114:115]
	v_pk_fma_f32 v[76:77], v[76:77], v[180:181], v[136:137] op_sel_hi:[1,0,1]
	v_pk_fma_f32 v[74:75], v[74:75], v[180:181], v[134:135] op_sel_hi:[1,0,1]
	v_pk_mul_f32 v[70:71], v[78:79], v[70:71]
	v_pk_add_f32 v[56:57], v[56:57], 1.0 op_sel_hi:[1,0]
	v_rcp_f32_e32 v38, v38
	v_rcp_f32_e32 v39, v39
	v_pk_add_f32 v[36:37], v[36:37], 1.0 op_sel_hi:[1,0]
	v_pk_add_f32 v[34:35], v[34:35], 1.0 op_sel_hi:[1,0]
	v_exp_f32_e32 v24, v24
	v_exp_f32_e32 v25, v25
	v_pk_fma_f32 v[8:9], v[8:9], v[146:147], v[140:141] op_sel_hi:[1,0,1]
	v_exp_f32_e32 v2, v2
	v_exp_f32_e32 v4, v4
	v_exp_f32_e32 v5, v5
	v_exp_f32_e32 v3, v3
	v_pk_mul_f32 v[88:89], v[96:97], v[88:89]
	v_pk_mul_f32 v[76:77], v[76:77], v[68:69]
	v_cvt_pk_bf16_f32 v83, v88, v89
	v_cvt_pk_bf16_f32 v84, v84, v85
	v_cvt_pk_bf16_f32 v85, v92, v93
	global_store_dwordx4 v[86:87], v[82:85], off
	v_pk_mul_f32 v[68:69], v[74:75], v[66:67]
	v_cvt_pk_bf16_f32 v66, v70, v71
	v_lshl_add_u64 v[70:71], s[98:99], 0, v[172:173]
	v_pk_fma_f32 v[62:63], v[62:63], v[152:153], v[142:143] op_sel_hi:[1,0,1]
	v_rcp_f32_e32 v56, v56
	v_rcp_f32_e32 v57, v57
	v_rcp_f32_e32 v34, v34
	v_rcp_f32_e32 v36, v36
	v_rcp_f32_e32 v37, v37
	v_rcp_f32_e32 v35, v35
	v_pk_add_f32 v[22:23], v[22:23], 1.0 op_sel_hi:[1,0]
	v_pk_mul_f32 v[8:9], v[8:9], s[78:79] op_sel_hi:[1,0]
	v_pk_fma_f32 v[80:81], v[80:81], v[180:181], v[144:145] op_sel_hi:[1,0,1]
	v_lshl_add_u64 v[70:71], v[70:71], 0, v[114:115]
	v_pk_fma_f32 v[60:61], v[60:61], v[152:153], v[136:137] op_sel_hi:[1,0,1]
	v_pk_fma_f32 v[58:59], v[58:59], v[152:153], v[134:135] op_sel_hi:[1,0,1]
	v_pk_mul_f32 v[54:55], v[62:63], v[54:55]
	v_pk_add_f32 v[40:41], v[40:41], 1.0 op_sel_hi:[1,0]
	v_rcp_f32_e32 v22, v22
	v_rcp_f32_e32 v23, v23
	v_pk_add_f32 v[20:21], v[20:21], 1.0 op_sel_hi:[1,0]
	v_pk_add_f32 v[18:19], v[18:19], 1.0 op_sel_hi:[1,0]
	v_exp_f32_e32 v8, v8
	v_exp_f32_e32 v9, v9
	v_pk_mul_f32 v[72:73], v[80:81], v[72:73]
	v_pk_mul_f32 v[60:61], v[60:61], v[52:53]
	v_cvt_pk_bf16_f32 v67, v72, v73
	v_cvt_pk_bf16_f32 v68, v68, v69
	v_cvt_pk_bf16_f32 v69, v76, v77
	global_store_dwordx4 v[70:71], v[66:69], off
	v_pk_mul_f32 v[52:53], v[58:59], v[50:51]
	v_cvt_pk_bf16_f32 v50, v54, v55
	v_lshl_add_u64 v[54:55], s[98:99], 0, v[170:171]
	v_pk_fma_f32 v[46:47], v[46:47], v[150:151], v[142:143] op_sel_hi:[1,0,1]
	v_rcp_f32_e32 v40, v40
	v_rcp_f32_e32 v41, v41
	v_rcp_f32_e32 v18, v18
	v_rcp_f32_e32 v20, v20
	v_rcp_f32_e32 v21, v21
	v_rcp_f32_e32 v19, v19
	v_pk_add_f32 v[6:7], v[6:7], 1.0 op_sel_hi:[1,0]
	v_pk_fma_f32 v[64:65], v[64:65], v[152:153], v[144:145] op_sel_hi:[1,0,1]
	v_lshl_add_u64 v[54:55], v[54:55], 0, v[114:115]
	v_pk_fma_f32 v[44:45], v[44:45], v[150:151], v[136:137] op_sel_hi:[1,0,1]
	v_pk_fma_f32 v[42:43], v[42:43], v[150:151], v[134:135] op_sel_hi:[1,0,1]
	v_pk_mul_f32 v[38:39], v[46:47], v[38:39]
	v_pk_add_f32 v[24:25], v[24:25], 1.0 op_sel_hi:[1,0]
	v_rcp_f32_e32 v6, v6
	v_rcp_f32_e32 v7, v7
	v_pk_add_f32 v[4:5], v[4:5], 1.0 op_sel_hi:[1,0]
	v_pk_add_f32 v[2:3], v[2:3], 1.0 op_sel_hi:[1,0]
	v_pk_mul_f32 v[56:57], v[64:65], v[56:57]
	v_pk_mul_f32 v[44:45], v[44:45], v[36:37]
	v_cvt_pk_bf16_f32 v51, v56, v57
	v_cvt_pk_bf16_f32 v52, v52, v53
	v_cvt_pk_bf16_f32 v53, v60, v61
	global_store_dwordx4 v[54:55], v[50:53], off
	v_pk_mul_f32 v[36:37], v[42:43], v[34:35]
	v_cvt_pk_bf16_f32 v34, v38, v39
	v_lshl_add_u64 v[38:39], s[98:99], 0, v[168:169]
	v_pk_fma_f32 v[30:31], v[30:31], v[148:149], v[142:143] op_sel_hi:[1,0,1]
	v_rcp_f32_e32 v24, v24
	v_rcp_f32_e32 v25, v25
	v_rcp_f32_e32 v2, v2
	v_rcp_f32_e32 v4, v4
	v_rcp_f32_e32 v5, v5
	v_rcp_f32_e32 v3, v3
	v_pk_fma_f32 v[48:49], v[48:49], v[150:151], v[144:145] op_sel_hi:[1,0,1]
	v_lshl_add_u64 v[38:39], v[38:39], 0, v[114:115]
	v_pk_fma_f32 v[28:29], v[28:29], v[148:149], v[136:137] op_sel_hi:[1,0,1]
	v_pk_fma_f32 v[26:27], v[26:27], v[148:149], v[134:135] op_sel_hi:[1,0,1]
	v_pk_mul_f32 v[22:23], v[30:31], v[22:23]
	v_pk_add_f32 v[8:9], v[8:9], 1.0 op_sel_hi:[1,0]
	v_pk_mul_f32 v[40:41], v[48:49], v[40:41]
	v_pk_mul_f32 v[28:29], v[28:29], v[20:21]
	v_cvt_pk_bf16_f32 v35, v40, v41
	v_cvt_pk_bf16_f32 v36, v36, v37
	v_cvt_pk_bf16_f32 v37, v44, v45
	global_store_dwordx4 v[38:39], v[34:37], off
	v_pk_mul_f32 v[20:21], v[26:27], v[18:19]
	v_cvt_pk_bf16_f32 v18, v22, v23
	v_lshl_add_u64 v[22:23], s[98:99], 0, v[166:167]
	v_pk_fma_f32 v[14:15], v[14:15], v[146:147], v[142:143] op_sel_hi:[1,0,1]
	v_rcp_f32_e32 v8, v8
	v_rcp_f32_e32 v9, v9
	v_pk_fma_f32 v[32:33], v[32:33], v[148:149], v[144:145] op_sel_hi:[1,0,1]
	v_lshl_add_u64 v[22:23], v[22:23], 0, v[114:115]
	v_pk_fma_f32 v[12:13], v[12:13], v[146:147], v[136:137] op_sel_hi:[1,0,1]
	v_pk_fma_f32 v[10:11], v[10:11], v[146:147], v[134:135] op_sel_hi:[1,0,1]
	v_pk_mul_f32 v[6:7], v[14:15], v[6:7]
	v_pk_mul_f32 v[24:25], v[32:33], v[24:25]
	v_pk_mul_f32 v[12:13], v[12:13], v[4:5]
	v_cvt_pk_bf16_f32 v19, v24, v25
	v_cvt_pk_bf16_f32 v20, v20, v21
	v_cvt_pk_bf16_f32 v21, v28, v29
	global_store_dwordx4 v[22:23], v[18:21], off
	v_pk_mul_f32 v[4:5], v[10:11], v[2:3]
	v_cvt_pk_bf16_f32 v2, v6, v7
	v_lshl_add_u64 v[6:7], s[98:99], 0, v[164:165]
	v_pk_fma_f32 v[16:17], v[16:17], v[146:147], v[144:145] op_sel_hi:[1,0,1]
	v_lshl_add_u64 v[6:7], v[6:7], 0, v[114:115]
	v_pk_mul_f32 v[8:9], v[16:17], v[8:9]
	s_nop 0
	v_cvt_pk_bf16_f32 v3, v8, v9
	v_cvt_pk_bf16_f32 v4, v4, v5
	v_cvt_pk_bf16_f32 v5, v12, v13
	global_store_dwordx4 v[6:7], v[2:5], off
	s_andn2_b64 vcc, exec, s[4:5]
	s_mov_b64 s[0:1], -1
	s_cbranch_vccnz .LBB0_340

.LBB0_391:
	s_cmp_gt_i32 s31, 5
	s_cselect_b64 s[0:1], -1, 0
	s_and_b64 s[2:3], s[10:11], s[0:1]
	s_andn2_b64 vcc, exec, s[2:3]
	s_cbranch_vccnz .LBB0_425
	s_waitcnt vmcnt(0)
	v_cmp_eq_u32_e32 vcc, 0, v0
	s_waitcnt lgkmcnt(0)
	s_barrier
	v_mov_b32_e32 v1, s88
	ds_read_b32 v2, v1 offset:8
	s_waitcnt lgkmcnt(0)
	v_readfirstlane_b32 s98, v2
	s_cmp_eq_u32 s98, 1
	s_cbranch_scc1 .Llb_loc_s4
	s_and_saveexec_b64 s[2:3], vcc
	s_cbranch_execz .LBB0_424
	v_mov_b32_e32 v1, s88
	s_waitcnt vmcnt(0) expcnt(0) lgkmcnt(0)
	ds_read_b32 v2, v1
	ds_read_b32 v1, v1 offset:4
	s_waitcnt lgkmcnt(1)
	v_cmp_ne_u32_e32 vcc, 0, v2
	s_cbranch_vccnz .LBB0_408
	v_readlane_b32 s4, v254, 8
	v_readlane_b32 s5, v254, 9
	s_load_dwordx2 s[8:9], s[4:5], 0x4
	s_add_u32 s4, s28, 0x4200
	s_addc_u32 s5, s29, 0
	s_add_u32 s6, s28, 0x4400
	s_addc_u32 s7, s29, 0
	s_waitcnt lgkmcnt(0)
	s_mul_i32 s16, s8, s25
	s_add_u32 s8, s28, 0x4500
	s_mul_i32 s16, s16, s9
	s_addc_u32 s9, s29, 0
	s_add_u32 s10, s28, 0x4600
	s_addc_u32 s11, s29, 0
	s_add_u32 s12, s28, 0x4700
	s_addc_u32 s13, s29, 0
	s_add_u32 s14, s28, 0x4800
	s_addc_u32 s15, s29, 0
	s_add_u32 s44, s28, 0x4900
	s_addc_u32 s45, s29, 0
	s_add_u32 s48, s28, 0x4a00
	s_addc_u32 s49, s29, 0
	s_add_u32 s50, s28, 0x4b00
	s_addc_u32 s51, s29, 0
	s_add_u32 s52, s28, 0x4c00
	s_addc_u32 s53, s29, 0
	s_add_u32 s66, s28, 0x4d00
	s_addc_u32 s67, s29, 0
	s_add_u32 s68, s28, 0x4e00
	s_addc_u32 s69, s29, 0
	s_add_u32 s70, s28, 0x4f00
	s_addc_u32 s71, s29, 0
	s_add_u32 s72, s28, 0x5000
	s_addc_u32 s73, s29, 0
	s_add_u32 s74, s28, 0x5100
	s_addc_u32 s75, s29, 0
	s_add_u32 s76, s28, 0x5200
	s_addc_u32 s77, s29, 0
	s_add_u32 s78, s28, 0x5300
	s_addc_u32 s79, s29, 0
	s_mov_b32 s17, 1
	v_mov_b32_e32 v17, 0
	s_branch .LBB0_396

.Llb_loc_s4:
	s_and_saveexec_b64 s[2:3], vcc
	s_cbranch_execz .Llb_done_s4
	v_mov_b32_e32 v1, s88
	ds_read_b32 v2, v1
	v_readlane_b32 s4, v254, 14
	v_readlane_b32 s10, v254, 12
	v_readlane_b32 s11, v254, 13
	s_lshl_b32 s4, s4, 8
	s_add_u32 s4, s10, s4
	s_addc_u32 s5, s11, 0
	v_mov_b32_e32 v3, 0x2400
	v_mov_b32_e32 v4, 1
	global_atomic_add v3, v4, s[4:5]
	s_waitcnt lgkmcnt(0)
	v_mul_lo_u32 v2, v2, 3
	s_mov_b32 s99, 0

.LBB0_425:
	s_cmp_lt_i32 s30, 6
	s_cselect_b64 s[2:3], -1, 0
	s_add_u32 s4, s28, 0x15000000
	v_writelane_b32 v254, s4, 58
	s_addc_u32 s4, s29, 0
	s_and_b64 s[26:27], s[2:3], s[0:1]
	v_writelane_b32 v254, s4, 61
	s_andn2_b64 vcc, exec, s[26:27]
	s_cbranch_vccnz .LBB0_518
	s_lshl_b32 s16, s18, 7
	s_and_b32 s8, s16, 0x180
	s_waitcnt vmcnt(0)
	v_mbcnt_lo_u32_b32 v140, -1, 0
	v_mbcnt_hi_u32_b32 v140, -1, v140
	v_readlane_b32 s60, v254, 15
	v_lshlrev_b32_e32 v106, 1, v140
	v_add_u32_e32 v104, s8, v106
	v_ashrrev_i32_e32 v105, 31, v104
	s_waitcnt lgkmcnt(0)
	v_lshlrev_b64 v[2:3], 2, v[104:105]
	v_readlane_b32 s62, v254, 17
	v_readlane_b32 s63, v254, 18
	s_movk_i32 s0, 0x1000
	v_readlane_b32 s64, v254, 19
	v_lshl_add_u64 v[4:5], s[62:63], 0, v[2:3]
	v_add_co_u32_e32 v6, vcc, s0, v4
	s_movk_i32 s0, 0x2000
	s_nop 0
	v_addc_co_u32_e32 v7, vcc, 0, v5, vcc
	v_add_co_u32_e32 v8, vcc, s0, v4
	s_movk_i32 s0, 0x3000
	s_nop 0
	v_addc_co_u32_e32 v9, vcc, 0, v5, vcc
	v_add_co_u32_e32 v10, vcc, s0, v4
	s_movk_i32 s0, 0x4000
	s_nop 0
	v_addc_co_u32_e32 v11, vcc, 0, v5, vcc
	v_add_co_u32_e32 v12, vcc, s0, v4
	s_movk_i32 s0, 0x5000
	s_nop 0
	v_addc_co_u32_e32 v13, vcc, 0, v5, vcc
	global_load_dwordx2 v[34:35], v[8:9], off offset:-4096
	global_load_dwordx2 v[36:37], v[8:9], off
	global_load_dwordx2 v[38:39], v[8:9], off offset:2048
	global_load_dwordx2 v[40:41], v[12:13], off offset:-4096
	global_load_dwordx2 v[42:43], v[4:5], off
	global_load_dwordx2 v[44:45], v[4:5], off offset:2048
	global_load_dwordx2 v[46:47], v[6:7], off offset:2048
	global_load_dwordx2 v[48:49], v[10:11], off offset:2048
	v_add_co_u32_e32 v6, vcc, s0, v4
	s_movk_i32 s0, 0x6000
	s_nop 0
	v_addc_co_u32_e32 v7, vcc, 0, v5, vcc
	v_add_co_u32_e32 v8, vcc, s0, v4
	s_movk_i32 s0, 0x7000
	s_nop 0
	v_addc_co_u32_e32 v9, vcc, 0, v5, vcc
	v_add_co_u32_e32 v10, vcc, s0, v4
	s_mov_b32 s0, 0x8000
	s_nop 0
	v_addc_co_u32_e32 v11, vcc, 0, v5, vcc
	global_load_dwordx2 v[50:51], v[12:13], off
	global_load_dwordx2 v[52:53], v[12:13], off offset:2048
	global_load_dwordx2 v[54:55], v[8:9], off offset:-4096
	global_load_dwordx2 v[56:57], v[8:9], off
	v_add_co_u32_e32 v12, vcc, s0, v4
	s_mov_b32 s0, 0x9000
	s_nop 0
	v_addc_co_u32_e32 v13, vcc, 0, v5, vcc
	global_load_dwordx2 v[58:59], v[8:9], off offset:2048
	global_load_dwordx2 v[60:61], v[12:13], off offset:-4096
	global_load_dwordx2 v[62:63], v[12:13], off
	global_load_dwordx2 v[64:65], v[12:13], off offset:2048
	v_add_co_u32_e32 v8, vcc, s0, v4
	s_mov_b32 s0, 0xa000
	s_nop 0
	v_addc_co_u32_e32 v9, vcc, 0, v5, vcc
	v_add_co_u32_e32 v12, vcc, s0, v4
	s_mov_b32 s0, 0xb000
	s_nop 0
	v_addc_co_u32_e32 v13, vcc, 0, v5, vcc
	v_add_co_u32_e32 v14, vcc, s0, v4
	s_mov_b32 s0, 0xc000
	s_nop 0
	v_addc_co_u32_e32 v15, vcc, 0, v5, vcc
	v_add_co_u32_e32 v16, vcc, s0, v4
	s_mov_b32 s0, 0xd000
	s_nop 0
	v_addc_co_u32_e32 v17, vcc, 0, v5, vcc
	global_load_dwordx2 v[66:67], v[12:13], off offset:-4096
	global_load_dwordx2 v[68:69], v[12:13], off
	global_load_dwordx2 v[70:71], v[12:13], off offset:2048
	global_load_dwordx2 v[72:73], v[16:17], off offset:-4096
	global_load_dwordx2 v[74:75], v[6:7], off offset:2048
	global_load_dwordx2 v[76:77], v[10:11], off offset:2048
	global_load_dwordx2 v[78:79], v[8:9], off offset:2048
	global_load_dwordx2 v[80:81], v[14:15], off offset:2048
	v_add_co_u32_e32 v6, vcc, s0, v4
	s_mov_b32 s0, 0xe000
	s_nop 0
	v_addc_co_u32_e32 v7, vcc, 0, v5, vcc
	v_add_co_u32_e32 v8, vcc, s0, v4
	v_readlane_b32 s65, v254, 20
	s_nop 0
	v_addc_co_u32_e32 v9, vcc, 0, v5, vcc
	v_add_co_u32_e32 v4, vcc, 0xf000, v4
	global_load_dwordx2 v[82:83], v[16:17], off
	global_load_dwordx2 v[84:85], v[16:17], off offset:2048
	global_load_dwordx2 v[86:87], v[8:9], off offset:-4096
	global_load_dwordx2 v[88:89], v[8:9], off
	global_load_dwordx2 v[90:91], v[8:9], off offset:2048
	v_addc_co_u32_e32 v5, vcc, 0, v5, vcc
	v_readlane_b32 s66, v254, 21
	v_readlane_b32 s67, v254, 22
	v_readlane_b32 s68, v254, 23
	v_readlane_b32 s69, v254, 24
	global_load_dwordx2 v[92:93], v[6:7], off offset:2048
	global_load_dwordx2 v[94:95], v[4:5], off
	v_lshl_add_u64 v[4:5], s[64:65], 0, v[2:3]
	global_load_dwordx2 v[96:97], v[4:5], off
	v_lshl_add_u64 v[4:5], s[66:67], 0, v[2:3]
	v_lshl_add_u64 v[2:3], s[68:69], 0, v[2:3]
	global_load_dwordx2 v[98:99], v[4:5], off
	global_load_dwordx2 v[100:101], v[2:3], off
	s_add_u32 s98, s28, 0xf000000
	s_addc_u32 s99, s29, 0
	s_lshl_b32 s17, s24, 5
	s_cmp_eq_u32 s25, 0x100
	s_cbranch_scc0 .Lp5_noremap_a
	s_and_b32 s17, s24, 7
	s_lshl_b32 s17, s17, 12
	s_lshr_b32 s0, s24, 3
	s_lshl_b32 s0, s0, 5
	s_add_i32 s17, s17, s0
.Lp5_noremap_a:
	s_and_b32 s0, s17, 0xfe0
	s_sub_i32 s9, s0, 30
	v_lshrrev_b32_e32 v1, 6, v0
	s_cmpk_lt_i32 s24, 0x400
	v_lshlrev_b32_e32 v105, 4, v0
	v_mov_b32_e32 v2, 0
	v_add_u32_e32 v3, s9, v1
	s_cselect_b64 s[6:7], -1, 0
	v_and_b32_e32 v4, 0x3f0, v105
	v_mov_b32_e32 v5, v2
	v_cmp_lt_i32_e32 vcc, -1, v3
	s_and_b32 s10, s17, 0xfffff000
	v_lshl_add_u64 v[102:103], s[98:99], 0, v[4:5]
	s_and_b64 s[2:3], s[6:7], vcc
	v_mov_b32_e32 v6, 0
	v_mov_b32_e32 v7, 0
	v_mov_b32_e32 v8, 0
	v_mov_b32_e32 v9, 0
	v_readlane_b32 s61, v254, 16
	v_readlane_b32 s70, v254, 25
	v_readlane_b32 s71, v254, 26
	v_readlane_b32 s72, v254, 27
	v_readlane_b32 s73, v254, 28
	v_readlane_b32 s74, v254, 29
	v_readlane_b32 s75, v254, 30
	s_and_saveexec_b64 s[0:1], s[2:3]
	s_cbranch_execz .LBB0_428
	v_add_u32_e32 v4, s10, v3
	v_ashrrev_i32_e32 v5, 31, v4
	v_lshlrev_b64 v[4:5], 10, v[4:5]
	v_lshl_add_u64 v[4:5], v[102:103], 0, v[4:5]
	global_load_dwordx4 v[6:9], v[4:5], off

.LBB0_442:
	s_or_b64 exec, exec, s[0:1]
	s_and_b64 vcc, exec, s[6:7]
	s_cbranch_vccz .LBB0_470
	s_lshr_b32 s33, s19, 8
	v_and_b32_e32 v114, 0x3f0, v105
	s_lshl_b32 s0, s33, 14
	v_and_b32_e32 v115, 0x1c00, v105
	v_lshlrev_b32_e32 v105, 4, v107
	s_add_i32 s34, s0, 0
	s_add_i32 s14, s16, 0
	s_lshl_b32 s0, s8, 1
	v_readlane_b32 s1, v254, 58
	v_and_b32_e32 v107, 0x3c00, v105
	v_lshlrev_b32_e32 v105, 4, v108
	s_add_u32 s0, s1, s0
	v_readlane_b32 s1, v254, 61
	v_and_b32_e32 v108, 0x7c00, v105
	v_lshlrev_b32_e32 v105, 4, v109
	s_addc_u32 s1, s1, 0
	v_and_b32_e32 v109, 0x7c00, v105
	v_lshlrev_b32_e32 v105, 4, v110
	s_and_b32 s6, s16, 0xfffffe00
	v_lshlrev_b32_e32 v116, 1, v104
	v_and_b32_e32 v104, 8, v140
	v_and_b32_e32 v110, 0xbc00, v105
	v_lshlrev_b32_e32 v105, 4, v111
	s_add_i32 s35, s6, 0
	v_cmp_eq_u32_e64 s[6:7], 0, v104
	v_and_b32_e32 v104, 4, v140
	v_and_b32_e32 v111, 0xfc00, v105
	v_lshlrev_b32_e32 v105, 4, v112
	v_cmp_eq_u32_e64 s[8:9], 0, v104
	v_and_b32_e32 v104, 2, v140
	v_and_b32_e32 v112, 0xfc00, v105
	v_lshlrev_b32_e32 v105, 4, v113
	v_cmp_eq_u32_e64 s[10:11], 0, v104
	v_and_b32_e32 v104, 1, v140
	v_and_b32_e32 v113, 0xfc00, v105
	v_cmp_eq_u32_e64 s[12:13], 0, v104
	v_and_b32_e32 v104, 0xffffffc0, v106
	v_and_b32_e32 v105, 60, v106
	v_add3_u32 v148, s14, v104, v105
	v_and_b32_e32 v104, -8, v106
	v_add_u32_e32 v114, 0, v114
	v_and_b32_e32 v117, 3, v140
	v_ashrrev_i32_e32 v105, 31, v104
	v_cmp_gt_i32_e64 s[14:15], 16, v140
	v_lshl_add_u64 v[104:105], v[104:105], 1, s[0:1]
	v_lshl_add_u32 v149, v140, 2, s35
	v_lshl_or_b32 v150, s33, 4, v117
	s_lshl_b32 s33, s25, 5
	s_cmp_eq_u32 s25, 0x100
	s_cbranch_scc0 .Lp5_noremap_b
	s_movk_i32 s33, 0x400
.Lp5_noremap_b:
	v_add_u32_e32 v151, v114, v115
	v_add_u32_e32 v152, v114, v107
	v_add_u32_e32 v153, v114, v108
	v_add_u32_e32 v154, v114, v109
	v_add_u32_e32 v155, v114, v110
	v_add_u32_e32 v156, v114, v111
	v_add_u32_e32 v157, v114, v112
	v_add_u32_e32 v158, v114, v113
	v_add_u32_e32 v159, s34, v116
	s_mov_b32 s48, 0x3b000000
	s_mov_b32 s44, 0x800000
	s_movk_i32 s45, 0x2000
	s_movk_i32 s49, 0x4000
	s_mov_b32 s58, s24
	s_branch .LBB0_445

.LBB0_470:
	s_ashr_i32 s71, s25, 3
	s_abs_i32 s0, s71
	v_cvt_f32_u32_e32 v1, s0
	s_sub_i32 s3, 0, s0
	s_abs_i32 s1, s24
	s_xor_b32 s2, s24, s71
	v_rcp_iflag_f32_e32 v1, v1
	s_ashr_i32 s2, s2, 31
	s_barrier
	v_mul_f32_e32 v1, 0x4f7ffffe, v1
	v_cvt_u32_f32_e32 v1, v1
	s_nop 0
	v_readfirstlane_b32 s4, v1
	s_mul_i32 s3, s3, s4
	s_mul_hi_u32 s3, s4, s3
	s_add_i32 s4, s4, s3
	s_mul_hi_u32 s3, s1, s4
	s_mul_i32 s4, s3, s0
	s_sub_i32 s1, s1, s4
	s_add_i32 s5, s3, 1
	s_sub_i32 s4, s1, s0
	s_cmp_ge_u32 s1, s0
	s_cselect_b32 s3, s5, s3
	s_cselect_b32 s1, s4, s1
	s_add_i32 s4, s3, 1
	s_cmp_ge_u32 s1, s0
	s_cselect_b32 s0, s4, s3
	s_xor_b32 s0, s0, s2
	s_sub_i32 s0, s0, s2
	s_mul_i32 s1, s0, s71
	s_sub_i32 s48, s24, s1
	s_and_b32 s0, s24, 7
	s_lshr_b32 s48, s24, 3
	s_cmp_gt_i32 s48, 63
	s_cbranch_scc1 .LBB0_517
	s_and_b32 s4, s19, 0xffffffc0
	s_waitcnt vmcnt(0)
	v_and_b32_e32 v4, 31, v140
	v_readlane_b32 s80, v254, 41
	v_or_b32_e32 v82, s4, v4
	v_readlane_b32 s84, v254, 45
	v_readlane_b32 s85, v254, 46
	v_ashrrev_i32_e32 v83, 31, v82
	v_readlane_b32 s86, v254, 47
	v_readlane_b32 s87, v254, 48
	s_mov_b64 s[40:41], s[84:85]
	v_lshlrev_b64 v[6:7], 2, v[82:83]
	s_mov_b64 s[42:43], s[86:87]
	v_lshl_add_u64 v[2:3], s[42:43], 0, v[6:7]
	global_load_dword v1, v[2:3], off offset:128
	global_load_dword v5, v[2:3], off
	s_mov_b32 s42, 0xbfb8aa3b
	s_mov_b32 s14, 0x42ce8ed0
	s_mov_b32 s15, 0xc2b17218
	v_mov_b32_e32 v24, 0x7f800000
	s_mov_b32 s35, 0x3f2aaaab
	v_mov_b32_e32 v25, 0x3ecc95a3
	v_mov_b32_e32 v2, 0x3f317218
	s_mov_b32 s34, 0x3f317218
	s_mov_b32 s1, 0x7f800000
	s_mov_b32 s33, 0x33800000
	v_readlane_b32 s81, v254, 42
	s_mov_b64 s[36:37], s[80:81]
	v_lshl_add_u64 v[8:9], s[40:41], 0, v[6:7]
	v_lshl_add_u64 v[6:7], s[36:37], 0, v[6:7]
	global_load_dword v88, v[8:9], off offset:128
	global_load_dword v90, v[8:9], off
	global_load_dword v92, v[6:7], off offset:128
	global_load_dword v94, v[6:7], off
	v_mov_b32_e32 v26, 0x3f2aaada
	s_mul_i32 s2, s18, 0x4200
	s_ashr_i32 s5, s4, 31
	s_add_i32 s43, s2, 0
	v_readlane_b32 s82, v254, 43
	v_readlane_b32 s83, v254, 44
	v_readlane_b32 s88, v254, 49
	v_readlane_b32 s89, v254, 50
	v_readlane_b32 s90, v254, 51
	v_readlane_b32 s91, v254, 52
	v_readlane_b32 s92, v254, 53
	v_readlane_b32 s93, v254, 54
	v_readlane_b32 s94, v254, 55
	v_readlane_b32 s95, v254, 56
	s_add_u32 s50, s28, 0x700000
	s_addc_u32 s51, s29, 0
	s_lshl_b64 s[8:9], s[4:5], 1
	v_readlane_b32 s80, v254, 15
	s_add_u32 s2, s57, s8
	v_readlane_b32 s90, v254, 25
	v_readlane_b32 s91, v254, 26
	s_addc_u32 s3, s56, s9
	s_lshl_b64 s[4:5], s[4:5], 2
	s_mov_b64 s[10:11], s[90:91]
	v_readlane_b32 s92, v254, 27
	v_readlane_b32 s93, v254, 28
	s_add_u32 s10, s10, s4
	s_mov_b64 s[12:13], s[92:93]
	s_addc_u32 s11, s11, s5
	s_add_u32 s12, s12, s4
	s_addc_u32 s13, s13, s5
	v_readlane_b32 s4, v254, 31
	s_add_u32 s6, s54, s8
	v_mov_b32_e32 v99, 0
	v_readlane_b32 s5, v254, 32
	s_addc_u32 s7, s55, s9
	s_add_i32 s17, s71, -1
	v_ashrrev_i32_e32 v84, 3, v140
	v_lshlrev_b32_e32 v182, 7, v84
	v_add_u32_e32 v134, 8, v84
	v_add_u32_e32 v136, 16, v84
	v_add_u32_e32 v138, 24, v84
	v_add_u32_e32 v142, 40, v84
	v_add_u32_e32 v144, 48, v84
	v_add_u32_e32 v146, 56, v84
	s_mov_b32 s46, 0
	v_readlane_b32 s81, v254, 16
	v_readlane_b32 s82, v254, 17
	v_readlane_b32 s83, v254, 18
	v_readlane_b32 s88, v254, 23
	v_readlane_b32 s89, v254, 24
	s_mov_b32 s47, 1
	v_ashrrev_i32_e32 v85, 31, v84
	v_ashrrev_i32_e32 v135, 31, v134
	v_ashrrev_i32_e32 v137, 31, v136
	v_ashrrev_i32_e32 v139, 31, v138
	v_ashrrev_i32_e32 v143, 31, v142
	v_ashrrev_i32_e32 v145, 31, v144
	v_ashrrev_i32_e32 v147, 31, v146
	s_mov_b64 s[56:57], 0x2000
	s_mov_b64 s[58:59], 0x4000
	s_mov_b64 s[60:61], 0x6000
	s_mov_b64 s[62:63], 0x8000
	s_waitcnt vmcnt(5)
	v_mul_f32_e32 v3, 0xbfb8aa3b, v1
	v_fma_f32 v10, v1, s42, -v3
	v_rndne_f32_e32 v11, v3
	v_fmac_f32_e32 v10, 0xb2a5705f, v1
	v_sub_f32_e32 v3, v3, v11
	v_add_f32_e32 v3, v3, v10
	v_cvt_i32_f32_e32 v11, v11
	v_exp_f32_e32 v3, v3
	v_cmp_nlt_f32_e32 vcc, s14, v1
	s_waitcnt vmcnt(4)
	v_mul_f32_e32 v27, 0xbfb8aa3b, v5
	v_fma_f32 v28, v5, s42, -v27
	v_ldexp_f32 v3, v3, v11
	v_cndmask_b32_e32 v3, 0, v3, vcc
	v_cmp_ngt_f32_e32 vcc, s15, v1
	v_fmac_f32_e32 v28, 0xb2a5705f, v5
	s_waitcnt vmcnt(2)
	v_mov_b32_e32 v91, v90
	v_cndmask_b32_e32 v1, v24, v3, vcc
	v_add_f32_e32 v3, 1.0, v1
	v_cvt_f64_f32_e32 v[10:11], v3
	v_frexp_mant_f32_e32 v12, v3
	v_add_f32_e32 v13, -1.0, v3
	v_frexp_exp_i32_f64_e32 v10, v[10:11]
	v_cmp_gt_f32_e32 vcc, s35, v12
	v_sub_f32_e32 v11, v1, v13
	v_sub_f32_e32 v13, v13, v3
	v_subbrev_co_u32_e32 v12, vcc, 0, v10, vcc
	v_add_f32_e32 v13, 1.0, v13
	v_cvt_f32_i32_e32 v10, v12
	v_sub_u32_e32 v12, 0, v12
	v_add_f32_e32 v11, v11, v13
	v_ldexp_f32 v3, v3, v12
	v_ldexp_f32 v11, v11, v12
	v_add_f32_e32 v12, -1.0, v3
	v_add_f32_e32 v14, 1.0, v3
	v_add_f32_e32 v13, 1.0, v12
	v_add_f32_e32 v15, -1.0, v14
	v_sub_f32_e32 v13, v3, v13
	v_sub_f32_e32 v3, v3, v15
	v_add_f32_e32 v3, v11, v3
	v_add_f32_e32 v15, v11, v13
	v_add_f32_e32 v11, v14, v3
	v_rcp_f32_e32 v18, v11
	v_add_f32_e32 v13, v12, v15
	v_sub_f32_e32 v14, v14, v11
	v_add_f32_e32 v3, v3, v14
	v_mul_f32_e32 v20, v13, v18
	v_mul_f32_e32 v14, v11, v20
	v_fma_f32 v16, v20, v11, -v14
	v_sub_f32_e32 v12, v12, v13
	v_fmac_f32_e32 v16, v20, v3
	v_add_f32_e32 v19, v15, v12
	v_add_f32_e32 v12, v14, v16
	v_sub_f32_e32 v15, v13, v12
	v_mov_b32_e32 v17, v12
	v_pk_add_f32 v[12:13], v[12:13], v[14:15] neg_lo:[0,1] neg_hi:[0,1]
	v_cmp_neq_f32_e32 vcc, s1, v1
	v_pk_add_f32 v[12:13], v[12:13], v[16:17] neg_lo:[0,1] neg_hi:[0,1]
	s_waitcnt vmcnt(0)
	v_mov_b32_e32 v95, v94
	v_add_f32_e32 v13, v19, v13
	v_add_f32_e32 v12, v12, v13
	v_add_f32_e32 v13, v15, v12
	v_mul_f32_e32 v17, v18, v13
	v_mul_f32_e32 v14, v11, v17
	v_sub_f32_e32 v15, v15, v13
	v_add_f32_e32 v19, v20, v17
	v_fma_f32 v16, v17, v11, -v14
	v_add_f32_e32 v21, v12, v15
	v_sub_f32_e32 v12, v19, v20
	v_fmac_f32_e32 v16, v17, v3
	v_sub_f32_e32 v11, v17, v12
	v_add_f32_e32 v12, v14, v16
	v_sub_f32_e32 v15, v13, v12
	v_mov_b32_e32 v17, v12
	v_pk_add_f32 v[12:13], v[12:13], v[14:15] neg_lo:[0,1] neg_hi:[0,1]
	v_mov_b32_e32 v116, v94
	v_pk_add_f32 v[12:13], v[12:13], v[16:17] neg_lo:[0,1] neg_hi:[0,1]
	v_mov_b32_e32 v117, v94
	v_add_f32_e32 v3, v21, v13
	v_add_f32_e32 v3, v12, v3
	v_add_f32_e32 v3, v15, v3
	v_mul_f32_e32 v3, v18, v3
	v_add_f32_e32 v3, v11, v3
	v_add_f32_e32 v11, v19, v3
	v_mul_f32_e32 v12, v11, v11
	v_sub_f32_e32 v14, v11, v19
	v_fmamk_f32 v15, v12, 0x3e9b6dac, v25
	v_ldexp_f32 v13, v11, 1
	v_mul_f32_e32 v11, v11, v12
	v_sub_f32_e32 v14, v3, v14
	v_fmaak_f32 v3, v12, v15, 0x3f2aaada
	v_ldexp_f32 v17, v14, 1
	v_pk_mul_f32 v[14:15], v[10:11], v[2:3]
	v_mov_b32_e32 v118, v90
	v_fma_f32 v12, v10, s34, -v14
	v_fmac_f32_e32 v12, 0xb102e308, v10
	v_pk_add_f32 v[10:11], v[14:15], v[12:13]
	v_mov_b32_e32 v16, v14
	v_sub_f32_e32 v3, v11, v13
	v_sub_f32_e32 v3, v15, v3
	v_add_f32_e32 v17, v17, v3
	v_pk_add_f32 v[18:19], v[10:11], v[14:15] neg_lo:[0,1] neg_hi:[0,1]
	v_pk_add_f32 v[14:15], v[10:11], v[16:17]
	v_mov_b32_e32 v13, v10
	v_mov_b32_e32 v19, v15
	v_pk_add_f32 v[22:23], v[12:13], v[18:19] neg_lo:[0,1] neg_hi:[0,1]
	v_pk_add_f32 v[12:13], v[12:13], v[18:19]
	v_mov_b32_e32 v21, v10
	v_pk_add_f32 v[18:19], v[12:13], v[10:11] op_sel:[1,0] op_sel_hi:[0,1] neg_lo:[0,1] neg_hi:[0,1]
	v_mov_b32_e32 v20, v17
	v_mov_b32_e32 v16, v15
	v_mov_b32_e32 v17, v13
	v_pk_mov_b32 v[10:11], v[10:11], v[18:19] op_sel:[1,0]
	v_pk_add_f32 v[14:15], v[14:15], v[18:19] op_sel_hi:[1,0] neg_lo:[0,1] neg_hi:[0,1]
	v_pk_add_f32 v[10:11], v[16:17], v[10:11] neg_lo:[0,1] neg_hi:[0,1]
	v_mov_b32_e32 v14, v22
	v_pk_add_f32 v[10:11], v[20:21], v[10:11] neg_lo:[0,1] neg_hi:[0,1]
	v_mov_b32_e32 v23, v13
	v_pk_add_f32 v[14:15], v[14:15], v[10:11]
	v_mov_b32_e32 v119, v90
	v_pk_add_f32 v[16:17], v[14:15], v[14:15] op_sel:[0,1] op_sel_hi:[1,0]
	v_mov_b32_e32 v93, v92
	v_pk_add_f32 v[12:13], v[12:13], v[16:17] op_sel:[1,0] op_sel_hi:[0,1]
	v_mov_b32_e32 v15, v12
	v_mov_b32_e32 v11, v16
	v_pk_add_f32 v[16:17], v[14:15], v[22:23] neg_lo:[0,1] neg_hi:[0,1]
	v_mov_b32_e32 v128, v92
	v_sub_f32_e32 v3, v14, v16
	v_pk_add_f32 v[10:11], v[10:11], v[16:17] neg_lo:[0,1] neg_hi:[0,1]
	v_sub_f32_e32 v3, v22, v3
	v_add_f32_e32 v3, v10, v3
	v_add_f32_e32 v3, v3, v11
	v_add_f32_e32 v3, v12, v3
	v_cndmask_b32_e32 v3, v24, v3, vcc
	v_cmp_lt_f32_e64 vcc, |v1|, s33
	v_mov_b32_e32 v129, v92
	v_mov_b32_e32 v89, v88
	v_cndmask_b32_e32 v1, v3, v1, vcc
	v_mul_f32_e32 v86, 0xc138aa3b, v1
	v_rndne_f32_e32 v1, v27
	v_sub_f32_e32 v3, v27, v1
	v_add_f32_e32 v3, v3, v28
	v_exp_f32_e32 v3, v3
	v_cvt_i32_f32_e32 v1, v1
	v_cmp_nlt_f32_e32 vcc, s14, v5
	v_mov_b32_e32 v130, v88
	v_mov_b32_e32 v131, v88
	v_ldexp_f32 v1, v3, v1
	v_cndmask_b32_e32 v1, 0, v1, vcc
	v_cmp_ngt_f32_e32 vcc, s15, v5
	v_mov_b32_e32 v87, v86
	v_mov_b32_e32 v132, v86
	v_cndmask_b32_e32 v1, v24, v1, vcc
	v_add_f32_e32 v3, 1.0, v1
	v_cvt_f64_f32_e32 v[6:7], v3
	v_frexp_exp_i32_f64_e32 v5, v[6:7]
	v_frexp_mant_f32_e32 v6, v3
	v_cmp_gt_f32_e32 vcc, s35, v6
	v_add_f32_e32 v8, -1.0, v3
	v_sub_f32_e32 v9, v1, v8
	v_subbrev_co_u32_e32 v5, vcc, 0, v5, vcc
	v_cvt_f32_i32_e32 v6, v5
	v_sub_u32_e32 v5, 0, v5
	v_ldexp_f32 v7, v3, v5
	v_sub_f32_e32 v3, v8, v3
	v_add_f32_e32 v3, 1.0, v3
	v_add_f32_e32 v13, -1.0, v7
	v_add_f32_e32 v3, v9, v3
	v_add_f32_e32 v8, 1.0, v7
	v_ldexp_f32 v3, v3, v5
	v_add_f32_e32 v5, 1.0, v13
	v_add_f32_e32 v9, -1.0, v8
	v_sub_f32_e32 v5, v7, v5
	v_sub_f32_e32 v7, v7, v9
	v_add_f32_e32 v5, v3, v5
	v_add_f32_e32 v3, v3, v7
	v_add_f32_e32 v7, v8, v3
	v_rcp_f32_e32 v16, v7
	v_add_f32_e32 v9, v13, v5
	v_sub_f32_e32 v8, v8, v7
	v_add_f32_e32 v3, v3, v8
	v_mul_f32_e32 v17, v9, v16
	v_mul_f32_e32 v10, v7, v17
	v_fma_f32 v12, v17, v7, -v10
	v_fmac_f32_e32 v12, v17, v3
	v_add_f32_e32 v8, v10, v12
	v_sub_f32_e32 v11, v9, v8
	v_sub_f32_e32 v13, v13, v9
	v_add_f32_e32 v5, v5, v13
	v_pk_add_f32 v[14:15], v[8:9], v[10:11] neg_lo:[0,1] neg_hi:[0,1]
	v_mov_b32_e32 v13, v8
	v_pk_add_f32 v[8:9], v[14:15], v[12:13] neg_lo:[0,1] neg_hi:[0,1]
	v_cmp_neq_f32_e32 vcc, s1, v1
	v_add_f32_e32 v5, v5, v9
	v_add_f32_e32 v5, v8, v5
	v_add_f32_e32 v9, v11, v5
	v_mul_f32_e32 v8, v16, v9
	v_add_f32_e32 v18, v17, v8
	v_sub_f32_e32 v10, v18, v17
	v_mul_f32_e32 v12, v7, v8
	v_sub_f32_e32 v17, v8, v10
	v_fma_f32 v10, v8, v7, -v12
	v_fmac_f32_e32 v10, v8, v3
	v_add_f32_e32 v8, v12, v10
	v_sub_f32_e32 v13, v9, v8
	v_sub_f32_e32 v3, v11, v9
	v_pk_add_f32 v[14:15], v[8:9], v[12:13] neg_lo:[0,1] neg_hi:[0,1]
	v_mov_b32_e32 v11, v8
	v_add_f32_e32 v3, v5, v3
	v_pk_add_f32 v[8:9], v[14:15], v[10:11] neg_lo:[0,1] neg_hi:[0,1]
	s_ashr_i32 s1, s0, 31
	v_add_f32_e32 v3, v3, v9
	v_add_f32_e32 v3, v8, v3
	v_add_f32_e32 v3, v13, v3
	v_mul_f32_e32 v3, v16, v3
	v_add_f32_e32 v3, v17, v3
	v_add_f32_e32 v5, v18, v3
	v_mul_f32_e32 v8, v5, v5
	v_ldexp_f32 v9, v5, 1
	v_mul_f32_e32 v7, v5, v8
	v_fmac_f32_e32 v25, 0x3e9b6dac, v8
	v_sub_f32_e32 v5, v5, v18
	v_fmac_f32_e32 v26, v8, v25
	v_sub_f32_e32 v3, v3, v5
	v_ldexp_f32 v5, v3, 1
	v_mov_b32_e32 v3, v26
	v_pk_mul_f32 v[2:3], v[6:7], v[2:3]
	s_lshl_b64 s[36:37], s[0:1], 12
	v_fma_f32 v8, v6, s34, -v2
	v_fmac_f32_e32 v8, 0xb102e308, v6
	v_pk_add_f32 v[6:7], v[2:3], v[8:9]
	v_mov_b32_e32 v10, v2
	v_sub_f32_e32 v9, v7, v9
	v_sub_f32_e32 v9, v3, v9
	v_add_f32_e32 v11, v5, v9
	v_pk_add_f32 v[2:3], v[6:7], v[2:3] neg_lo:[0,1] neg_hi:[0,1]
	v_pk_add_f32 v[12:13], v[6:7], v[10:11]
	v_mov_b32_e32 v9, v6
	v_mov_b32_e32 v3, v13
	v_pk_add_f32 v[14:15], v[8:9], v[2:3] neg_lo:[0,1] neg_hi:[0,1]
	v_pk_add_f32 v[2:3], v[8:9], v[2:3]
	v_mov_b32_e32 v10, v11
	v_pk_add_f32 v[8:9], v[2:3], v[6:7] op_sel:[1,0] op_sel_hi:[0,1] neg_lo:[0,1] neg_hi:[0,1]
	v_pk_add_f32 v[16:17], v[12:13], v[8:9] op_sel_hi:[1,0] neg_lo:[0,1] neg_hi:[0,1]
	v_mov_b32_e32 v12, v13
	v_mov_b32_e32 v13, v3
	v_pk_mov_b32 v[8:9], v[6:7], v[8:9] op_sel:[1,0]
	v_mov_b32_e32 v11, v6
	v_pk_add_f32 v[8:9], v[12:13], v[8:9] neg_lo:[0,1] neg_hi:[0,1]
	v_mov_b32_e32 v16, v14
	v_pk_add_f32 v[6:7], v[10:11], v[8:9] neg_lo:[0,1] neg_hi:[0,1]
	v_mov_b32_e32 v15, v3
	v_pk_add_f32 v[8:9], v[16:17], v[6:7]
	v_and_b32_e32 v5, 7, v140
	v_pk_add_f32 v[10:11], v[8:9], v[8:9] op_sel:[0,1] op_sel_hi:[1,0]
	v_lshlrev_b32_e32 v98, 4, v5
	v_pk_add_f32 v[2:3], v[2:3], v[10:11] op_sel:[1,0] op_sel_hi:[0,1]
	v_mov_b32_e32 v9, v2
	v_pk_add_f32 v[12:13], v[8:9], v[14:15] neg_lo:[0,1] neg_hi:[0,1]
	v_mov_b32_e32 v7, v10
	v_sub_f32_e32 v3, v8, v12
	v_pk_add_f32 v[6:7], v[6:7], v[12:13] neg_lo:[0,1] neg_hi:[0,1]
	v_sub_f32_e32 v3, v14, v3
	v_add_f32_e32 v3, v6, v3
	v_add_f32_e32 v3, v3, v7
	v_add_f32_e32 v2, v2, v3
	v_cndmask_b32_e32 v2, v24, v2, vcc
	v_cmp_lt_f32_e64 vcc, |v1|, s33
	v_ashrrev_i32_e32 v3, 5, v140
	v_lshlrev_b32_e32 v6, 3, v3
	v_cndmask_b32_e32 v1, v2, v1, vcc
	v_or_b32_e32 v2, s16, v4
	v_ashrrev_i32_e32 v7, 31, v6
	v_lshlrev_b32_e32 v13, 4, v3
	v_lshl_add_u32 v15, v3, 9, s43
	v_ashrrev_i32_e32 v3, 31, v2
	v_lshl_add_u64 v[8:9], v[6:7], 1, s[4:5]
	v_lshlrev_b32_e32 v10, 5, v5
	v_mov_b32_e32 v11, v99
	v_sub_u32_e32 v184, v4, v6
	v_lshlrev_b64 v[6:7], 7, v[2:3]
	v_or_b32_e32 v2, 64, v2
	v_lshl_add_u64 v[102:103], s[10:11], 0, v[10:11]
	v_or_b32_e32 v14, 32, v4
	s_lshl_b64 s[10:11], s[0:1], 18
	v_ashrrev_i32_e32 v3, 31, v2
	v_lshl_add_u64 v[104:105], s[12:13], 0, v[10:11]
	v_or_b32_e32 v10, s16, v14
	s_add_u32 s10, s28, s10
	v_lshlrev_b64 v[2:3], 7, v[2:3]
	s_addc_u32 s11, s29, s11
	v_lshl_add_u64 v[110:111], v[8:9], 0, v[2:3]
	v_lshlrev_b32_e32 v2, 7, v140
	v_ashrrev_i32_e32 v11, 31, v10
	s_add_u32 s40, s10, 0x300000
	v_lshl_add_u64 v[108:109], v[8:9], 0, v[6:7]
	v_and_b32_e32 v6, 0xfffffc00, v2
	v_or_b32_e32 v7, 0x380, v2
	v_lshlrev_b64 v[2:3], 7, v[10:11]
	s_addc_u32 s41, s11, 0
	s_lshl_b64 s[52:53], s[0:1], 3
	s_mov_b64 s[0:1], 0x1000
	v_lshl_add_u64 v[122:123], v[8:9], 0, v[2:3]
	v_or_b32_e32 v2, 64, v10
	v_lshl_add_u64 v[112:113], v[102:103], 0, s[0:1]
	s_mov_b64 s[0:1], 0x1800
	v_ashrrev_i32_e32 v3, 31, v2
	s_cmp_eq_u32 s48, s17
	v_lshl_add_u64 v[114:115], v[102:103], 0, s[0:1]
	v_lshlrev_b64 v[2:3], 7, v[2:3]
	v_readlane_b32 s0, v254, 58
	v_lshl_add_u64 v[106:107], s[6:7], 0, v[98:99]
	v_cmp_gt_u32_e64 s[6:7], 32, v140
	s_cselect_b64 s[54:55], -1, 0
	v_lshl_add_u64 v[124:125], v[8:9], 0, v[2:3]
	v_lshlrev_b64 v[2:3], 3, v[82:83]
	v_add_u32_e32 v140, 32, v84
	s_add_u32 s0, s0, s8
	v_readlane_b32 s1, v254, 61
	v_mul_f32_e32 v96, 0xc138aa3b, v1
	v_add_u32_e32 v12, s43, v182
	v_add_u32_e32 v183, s43, v98
	v_lshl_add_u32 v5, v4, 7, s43
	v_lshl_add_u64 v[126:127], s[40:41], 0, v[2:3]
	v_lshlrev_b32_e32 v4, 1, v4
	v_lshlrev_b32_e32 v8, 1, v14
	v_lshlrev_b32_e32 v9, 7, v134
	v_lshlrev_b32_e32 v10, 7, v136
	v_lshlrev_b32_e32 v11, 7, v138
	v_lshlrev_b32_e32 v14, 7, v140
	v_lshlrev_b32_e32 v16, 7, v142
	v_lshlrev_b32_e32 v17, 7, v144
	v_lshlrev_b32_e32 v18, 7, v146
	v_lshl_add_u64 v[148:149], s[50:51], 0, v[2:3]
	s_addc_u32 s1, s1, s9
	v_mbcnt_lo_u32_b32 v2, -1, 0
	v_add_u32_e32 v1, -3, v84
	v_lshl_add_u64 v[100:101], s[2:3], 0, v[98:99]
	v_cmp_gt_i32_e64 s[2:3], 3, v84
	v_cmp_eq_u32_e64 s[4:5], 3, v84
	v_mov_b32_e32 v97, v96
	v_mov_b32_e32 v120, v96
	v_mov_b32_e32 v121, v96
	v_mov_b32_e32 v133, v86
	v_add_u32_e32 v185, 32, v184
	v_ashrrev_i32_e32 v141, 31, v140
	v_lshl_add_u64 v[150:151], s[0:1], 0, v[98:99]
	s_add_i32 s73, s43, 0x400
	s_add_i32 s75, s43, 0x800
	s_add_i32 s81, s43, 0xc00
	s_add_i32 s88, s43, 0x1000
	s_mov_b64 s[64:65], 0xa000
	s_add_i32 s89, s43, 0x1400
	s_mov_b64 s[66:67], 0xc000
	s_add_i32 s44, s43, 0x1800
	s_mov_b64 s[68:69], 0xe000
	s_add_i32 s45, s43, 0x1c00
	s_add_i32 s33, s43, 0x2000
	v_add_u32_e32 v186, v12, v98
	v_add_u32_e32 v187, v183, v6
	v_add_u32_e32 v188, v183, v7
	s_mov_b32 s70, 0x3fb17218
	s_mov_b32 s72, 0xbab60b61
	s_mov_b32 s74, 0x39500d01
	s_mov_b32 s76, 0xbc088889
	s_mov_b32 s78, 0xbd2aaaab
	s_mov_b32 s80, 0xbe2aaaab
	s_brev_b32 s16, 1
	v_mbcnt_hi_u32_b32 v189, -1, v2
	s_mov_b64 s[82:83], 0xffffffff
	v_bfrev_b32_e32 v153, 1
	v_add_u32_e32 v190, v15, v4
	s_movk_i32 s17, 0x7fff
	v_add_u32_e32 v191, v15, v8
	v_add_u32_e32 v192, v183, v9
	v_add_u32_e32 v193, v183, v10
	v_add_u32_e32 v194, v183, v11
	v_add_u32_e32 v195, v183, v14
	v_add_u32_e32 v196, v183, v16
	v_add_u32_e32 v197, v183, v17
	v_add_u32_e32 v198, v183, v18
	v_mov_b32_e32 v248, v99
	v_mov_b32_e32 v249, v99
	v_mov_b32_e32 v250, v99
	v_mov_b32_e32 v251, v99
	v_add_u32_e32 v199, v5, v13
	v_mov_b32_e32 v200, 0x3f80
	s_mov_b32 s90, s46
	v_readlane_b32 s84, v254, 19
	v_readlane_b32 s85, v254, 20
	v_readlane_b32 s86, v254, 21
	v_readlane_b32 s87, v254, 22
	v_readlane_b32 s94, v254, 29
	v_readlane_b32 s95, v254, 30
	s_branch .LBB0_473

.LBB0_518:
	s_cmp_gt_u32 s31, 6
	s_cselect_b64 s[0:1], -1, 0
	s_and_b64 s[0:1], s[26:27], s[0:1]
	s_andn2_b64 vcc, exec, s[0:1]
	s_cbranch_vccnz .LBB0_552
	s_waitcnt vmcnt(0)
	v_cmp_eq_u32_e32 vcc, 0, v0
	s_waitcnt lgkmcnt(0)
	s_barrier
	v_mov_b32_e32 v1, s88
	ds_read_b32 v2, v1 offset:8
	s_waitcnt lgkmcnt(0)
	v_readfirstlane_b32 s98, v2
	s_cmp_eq_u32 s98, 1
	s_cbranch_scc1 .Llb_loc_s5
	s_and_saveexec_b64 s[0:1], vcc
	s_cbranch_execz .LBB0_551
	v_mov_b32_e32 v1, s88
	s_waitcnt vmcnt(0) expcnt(0) lgkmcnt(0)
	ds_read_b32 v2, v1
	ds_read_b32 v1, v1 offset:4
	s_waitcnt lgkmcnt(1)
	v_cmp_ne_u32_e32 vcc, 0, v2
	s_cbranch_vccnz .LBB0_535
	v_readlane_b32 s2, v254, 8
	v_readlane_b32 s3, v254, 9
	s_load_dwordx2 s[6:7], s[2:3], 0x4
	s_add_u32 s2, s28, 0x4200
	s_addc_u32 s3, s29, 0
	s_add_u32 s4, s28, 0x4400
	s_addc_u32 s5, s29, 0
	s_waitcnt lgkmcnt(0)
	s_mul_i32 s16, s6, s25
	s_add_u32 s6, s28, 0x4500
	s_mul_i32 s16, s16, s7
	s_addc_u32 s7, s29, 0
	s_add_u32 s8, s28, 0x4600
	s_addc_u32 s9, s29, 0
	s_add_u32 s10, s28, 0x4700
	s_addc_u32 s11, s29, 0
	s_add_u32 s12, s28, 0x4800
	s_addc_u32 s13, s29, 0
	s_add_u32 s14, s28, 0x4900
	s_addc_u32 s15, s29, 0
	s_add_u32 s36, s28, 0x4a00
	s_addc_u32 s37, s29, 0
	s_add_u32 s40, s28, 0x4b00
	s_addc_u32 s41, s29, 0
	s_add_u32 s42, s28, 0x4c00
	s_addc_u32 s43, s29, 0
	s_add_u32 s44, s28, 0x4d00
	s_addc_u32 s45, s29, 0
	s_add_u32 s48, s28, 0x4e00
	s_addc_u32 s49, s29, 0
	s_add_u32 s50, s28, 0x4f00
	s_addc_u32 s51, s29, 0
	s_add_u32 s52, s28, 0x5000
	s_addc_u32 s53, s29, 0
	s_add_u32 s54, s28, 0x5100
	s_addc_u32 s55, s29, 0
	s_add_u32 s56, s28, 0x5200
	s_addc_u32 s57, s29, 0
	s_add_u32 s58, s28, 0x5300
	s_addc_u32 s59, s29, 0
	s_mov_b32 s17, 1
	v_mov_b32_e32 v17, 0
	s_branch .LBB0_523

.LBB0_550:
	s_or_b64 exec, exec, s[2:3]
	s_waitcnt vmcnt(0)
	buffer_inv sc1
	s_waitcnt vmcnt(0)
.LBB0_551:
	s_or_b64 exec, exec, s[0:1]
	s_barrier
	s_branch .LBB0_552
.Llb_loc_s5:
	s_and_saveexec_b64 s[0:1], vcc
	s_cbranch_execz .Llb_done_s5
	v_mov_b32_e32 v1, s88
	ds_read_b32 v2, v1
	v_readlane_b32 s4, v254, 14
	v_readlane_b32 s10, v254, 12
	v_readlane_b32 s11, v254, 13
	s_lshl_b32 s4, s4, 8
	s_add_u32 s4, s10, s4
	s_addc_u32 s5, s11, 0
	v_mov_b32_e32 v3, 0x2400
	v_mov_b32_e32 v4, 1
	global_atomic_add v3, v4, s[4:5]
	v_mov_b32_e32 v5, 0x2408
	global_atomic_add v5, v4, s[10:11]
	s_waitcnt lgkmcnt(0)
	v_mul_lo_u32 v2, v2, 4
	s_mov_b32 s99, 0

.Llb_loc_s7:
	s_and_saveexec_b64 s[2:3], vcc
	s_cbranch_execz .Llb_done_s7
	v_mov_b32_e32 v1, s88
	ds_read_b32 v2, v1
	v_readlane_b32 s4, v254, 14
	v_readlane_b32 s10, v254, 12
	v_readlane_b32 s11, v254, 13
	s_lshl_b32 s4, s4, 8
	s_add_u32 s4, s10, s4
	s_addc_u32 s5, s11, 0
	v_mov_b32_e32 v3, 0x2400
	v_mov_b32_e32 v4, 1
	global_atomic_add v3, v4, s[4:5]
	s_waitcnt lgkmcnt(0)
	v_mul_lo_u32 v2, v2, 5
	s_mov_b32 s99, 0

.Llb_acq_s7:
	v_mov_b32_e32 v5, 0x2408
	s_mov_b32 s99, 0

.Llb_loc_s8:
	s_and_saveexec_b64 s[0:1], vcc
	s_cbranch_execz .Llb_done_s8
	v_mov_b32_e32 v1, s88
	ds_read_b32 v2, v1
	v_readlane_b32 s4, v254, 14
	v_readlane_b32 s10, v254, 12
	v_readlane_b32 s11, v254, 13
	s_lshl_b32 s4, s4, 8
	s_add_u32 s4, s10, s4
	s_addc_u32 s5, s11, 0
	v_mov_b32_e32 v3, 0x2400
	v_mov_b32_e32 v4, 1
	global_atomic_add v3, v4, s[4:5]
	s_waitcnt lgkmcnt(0)
	v_mul_lo_u32 v2, v2, 6
	s_mov_b32 s99, 0
